# stick-breaking exp block: five adjacent (1+e) add pairs merged into v_pk_add_f32
# speedup vs baseline: 1.0016x; 1.0016x over previous
.LBB0_704:
	s_waitcnt vmcnt(0)
	v_mfma_f32_32x32x16_bf16 v[32:47], v[110:113], v[74:77], 0
	v_sub_u32_e64 v64, s74, 1 clamp
	global_load_dwordx4 v[142:145], v[170:171], off
	global_load_dwordx4 v[138:141], v[170:171], off offset:1024
	global_load_dwordx4 v[134:137], v[170:171], off offset:2048
	global_load_dwordx4 v[130:133], v[170:171], off offset:3072
	v_mov_b64_e32 v[174:175], v[100:101]
	v_mov_b64_e32 v[172:173], v[98:99]
	s_cmp_lt_u32 s5, s6
	v_mfma_f32_32x32x16_bf16 v[48:63], v[102:105], v[74:77], 0
	v_mfma_f32_32x32x16_bf16 v[32:47], v[82:85], v[66:69], v[32:47]
	v_add_co_u32_e32 v82, vcc, s77, v170
	s_nop 1
	v_addc_co_u32_e32 v83, vcc, 0, v171, vcc
	global_load_dwordx4 v[126:129], v[82:83], off
	global_load_dwordx4 v[122:125], v[82:83], off offset:1024
	global_load_dwordx4 v[118:121], v[82:83], off offset:2048
	global_load_dwordx4 v[114:117], v[82:83], off offset:3072
	v_lshlrev_b64 v[82:83], 13, v[64:65]
	v_mfma_f32_32x32x16_bf16 v[48:63], v[86:89], v[66:69], v[48:63]
	v_mfma_f32_32x32x16_bf16 v[32:47], v[94:97], v[70:73], v[32:47]
	v_mfma_f32_32x32x16_bf16 v[48:63], v[90:93], v[70:73], v[48:63]
	v_lshl_add_u64 v[90:91], v[168:169], 0, v[82:83]
	v_add_co_u32_e32 v98, vcc, s77, v90
	global_load_dwordx4 v[110:113], v[90:91], off
	global_load_dwordx4 v[82:85], v[90:91], off offset:1024
	v_addc_co_u32_e32 v99, vcc, 0, v91, vcc
	v_mfma_f32_32x32x16_bf16 v[32:47], v[106:109], v[78:81], v[32:47]
	global_load_dwordx4 v[102:105], v[98:99], off
	global_load_dwordx4 v[86:89], v[98:99], off offset:1024
	global_load_dwordx4 v[94:97], v[90:91], off offset:2048
	global_load_dwordx4 v[106:109], v[90:91], off offset:3072
	s_nop 0
	global_load_dwordx4 v[90:93], v[98:99], off offset:2048
	s_nop 0
	global_load_dwordx4 v[98:101], v[98:99], off offset:3072
	s_nop 3
	v_med3_f32 v32, v32, s28, v225
	v_mfma_f32_32x32x16_bf16 v[48:63], v[172:175], v[78:81], v[48:63]
	v_med3_f32 v33, v33, s28, v225
	v_exp_f32_e32 v176, v32
	v_exp_f32_e32 v177, v33
	v_med3_f32 v34, v34, s28, v225
	v_exp_f32_e32 v178, v34
	v_med3_f32 v35, v35, s28, v225
	v_exp_f32_e32 v179, v35
	s_nop 4
	v_med3_f32 v32, v48, s28, v225
	v_exp_f32_e32 v174, v32
	v_med3_f32 v33, v49, s28, v225
	v_med3_f32 v34, v50, s28, v225
	v_add_f32_e32 v32, 1.0, v176
	v_exp_f32_e32 v175, v33
	v_add_f32_e32 v33, 1.0, v177
	v_exp_f32_e32 v180, v34
	v_med3_f32 v35, v51, s28, v225
	v_rcp_f32_e32 v32, v32
	v_rcp_f32_e32 v33, v33
	v_exp_f32_e32 v181, v35
	v_add_f32_e32 v48, 1.0, v174
	v_med3_f32 v36, v36, s28, v225
	v_rcp_f32_e32 v172, v48
	v_add_f32_e32 v48, 1.0, v175
	v_add_f32_e32 v50, 1.0, v180
	v_exp_f32_e32 v182, v36
	v_med3_f32 v36, v52, s28, v225
	v_med3_f32 v37, v37, s28, v225
	v_rcp_f32_e32 v173, v48
	v_pk_mul_f32 v[48:49], v[176:177], v[32:33]
	v_pk_add_f32 v[34:35], v[178:179], 1.0 op_sel_hi:[1,0]
	v_rcp_f32_e32 v176, v50
	v_add_f32_e32 v50, 1.0, v181
	v_exp_f32_e32 v184, v36
	v_exp_f32_e32 v183, v37
	v_med3_f32 v37, v53, s28, v225
	v_rcp_f32_e32 v34, v34
	v_rcp_f32_e32 v35, v35
	v_rcp_f32_e32 v177, v50
	v_exp_f32_e32 v185, v37
	v_med3_f32 v38, v38, s28, v225
	v_add_f32_e32 v52, 1.0, v184
	v_exp_f32_e32 v186, v38
	v_med3_f32 v38, v54, s28, v225
	v_med3_f32 v39, v39, s28, v225
	v_pk_mul_f32 v[50:51], v[178:179], v[34:35]
	v_pk_mul_f32 v[178:179], v[180:181], v[176:177]
	v_pk_add_f32 v[36:37], v[182:183], 1.0 op_sel_hi:[1,0]
	v_rcp_f32_e32 v180, v52
	v_add_f32_e32 v52, 1.0, v185
	v_exp_f32_e32 v188, v38
	v_exp_f32_e32 v187, v39
	v_med3_f32 v39, v55, s28, v225
	v_rcp_f32_e32 v36, v36
	v_rcp_f32_e32 v37, v37
	v_rcp_f32_e32 v181, v52
	v_exp_f32_e32 v189, v39
	v_med3_f32 v40, v40, s28, v225
	v_add_f32_e32 v54, 1.0, v188
	v_exp_f32_e32 v190, v40
	v_med3_f32 v40, v56, s28, v225
	v_med3_f32 v41, v41, s28, v225
	v_pk_mul_f32 v[52:53], v[182:183], v[36:37]
	v_pk_mul_f32 v[182:183], v[184:185], v[180:181]
	v_pk_add_f32 v[38:39], v[186:187], 1.0 op_sel_hi:[1,0]
	v_rcp_f32_e32 v184, v54
	v_add_f32_e32 v54, 1.0, v189
	v_exp_f32_e32 v192, v40
	v_exp_f32_e32 v191, v41
	v_med3_f32 v41, v57, s28, v225
	v_rcp_f32_e32 v38, v38
	v_rcp_f32_e32 v39, v39
	v_rcp_f32_e32 v185, v54
	v_exp_f32_e32 v193, v41
	v_med3_f32 v42, v42, s28, v225
	v_add_f32_e32 v56, 1.0, v192
	v_exp_f32_e32 v194, v42
	v_med3_f32 v42, v58, s28, v225
	v_med3_f32 v43, v43, s28, v225
	v_pk_mul_f32 v[54:55], v[186:187], v[38:39]
	v_pk_mul_f32 v[186:187], v[188:189], v[184:185]
	v_pk_add_f32 v[40:41], v[190:191], 1.0 op_sel_hi:[1,0]
	v_rcp_f32_e32 v188, v56
	v_add_f32_e32 v56, 1.0, v193
	v_exp_f32_e32 v196, v42
	v_exp_f32_e32 v195, v43
	v_med3_f32 v43, v59, s28, v225
	v_rcp_f32_e32 v40, v40
	v_rcp_f32_e32 v41, v41
	v_rcp_f32_e32 v189, v56
	v_exp_f32_e32 v197, v43
	v_add_f32_e32 v58, 1.0, v196
	v_pk_mul_f32 v[56:57], v[190:191], v[40:41]
	v_pk_mul_f32 v[190:191], v[192:193], v[188:189]
	v_pk_add_f32 v[42:43], v[194:195], 1.0 op_sel_hi:[1,0]
	v_rcp_f32_e32 v192, v58
	v_add_f32_e32 v58, 1.0, v197
	v_rcp_f32_e32 v42, v42
	v_rcp_f32_e32 v43, v43
	v_rcp_f32_e32 v193, v58
	v_med3_f32 v44, v44, s28, v225
	v_med3_f32 v45, v45, s28, v225
	v_exp_f32_e32 v200, v44
	v_exp_f32_e32 v201, v45
	v_med3_f32 v44, v60, s28, v225
	v_med3_f32 v46, v46, s28, v225
	v_pk_mul_f32 v[58:59], v[194:195], v[42:43]
	v_exp_f32_e32 v202, v44
	v_pk_mul_f32 v[194:195], v[196:197], v[192:193]
	v_med3_f32 v45, v61, s28, v225
	v_exp_f32_e32 v196, v46
	v_med3_f32 v46, v62, s28, v225
	v_med3_f32 v47, v47, s28, v225
	v_add_f32_e32 v44, 1.0, v200
	v_exp_f32_e32 v203, v45
	v_add_f32_e32 v45, 1.0, v201
	v_exp_f32_e32 v204, v46
	v_exp_f32_e32 v197, v47
	v_med3_f32 v47, v63, s28, v225
	v_rcp_f32_e32 v44, v44
	v_rcp_f32_e32 v45, v45
	v_exp_f32_e32 v205, v47
	v_add_f32_e32 v60, 1.0, v202
	v_rcp_f32_e32 v198, v60
	v_add_f32_e32 v60, 1.0, v203
	v_add_f32_e32 v62, 1.0, v204
	v_rcp_f32_e32 v199, v60
	v_pk_mul_f32 v[60:61], v[200:201], v[44:45]
	v_add_f32_e32 v46, 1.0, v196
	v_rcp_f32_e32 v200, v62
	v_add_f32_e32 v47, 1.0, v197
	v_add_f32_e32 v62, 1.0, v205
	v_rcp_f32_e32 v46, v46
	v_rcp_f32_e32 v47, v47
	v_rcp_f32_e32 v201, v62
	v_pk_mul_f32 v[174:175], v[174:175], v[172:173]
	v_pk_mul_f32 v[202:203], v[202:203], v[198:199]
	v_pk_mul_f32 v[62:63], v[196:197], v[46:47]
	v_pk_mul_f32 v[196:197], v[204:205], v[200:201]
	s_cbranch_scc1 .LBB0_703
	v_add_u32_e32 v167, s5, v152
	v_mov_b32_e32 v64, v228
	v_subrev_u32_e32 v204, 63, v167
	v_subrev_u32_e32 v205, 31, v167
	v_cmp_lt_i32_e32 vcc, v204, v64
	v_subrev_u32_e32 v204, 62, v167
	s_nop 0
	v_cndmask_b32_e32 v32, 1.0, v32, vcc
	v_cndmask_b32_e32 v48, 0, v48, vcc
	v_cmp_lt_i32_e32 vcc, v205, v64
	v_subrev_u32_e32 v205, 30, v167
	s_nop 0
	v_cndmask_b32_e32 v172, 1.0, v172, vcc
	v_cndmask_b32_e32 v174, 0, v174, vcc
	v_cmp_lt_i32_e32 vcc, v204, v64
	v_subrev_u32_e32 v204, 61, v167
	s_nop 0
	v_cndmask_b32_e32 v33, 1.0, v33, vcc
	v_cndmask_b32_e32 v49, 0, v49, vcc
	v_cmp_lt_i32_e32 vcc, v205, v64
	v_subrev_u32_e32 v205, 29, v167
	s_nop 0
	v_cndmask_b32_e32 v173, 1.0, v173, vcc
	v_cndmask_b32_e32 v175, 0, v175, vcc
	v_cmp_lt_i32_e32 vcc, v204, v64
	v_subrev_u32_e32 v204, 60, v167
	s_nop 0
	v_cndmask_b32_e32 v34, 1.0, v34, vcc
	v_cndmask_b32_e32 v50, 0, v50, vcc
	v_cmp_lt_i32_e32 vcc, v205, v64
	v_subrev_u32_e32 v205, 28, v167
	s_nop 0
	v_cndmask_b32_e32 v176, 1.0, v176, vcc
	v_cndmask_b32_e32 v178, 0, v178, vcc
	v_cmp_lt_i32_e32 vcc, v204, v64
	v_subrev_u32_e32 v204, 55, v167
	s_nop 0
	v_cndmask_b32_e32 v35, 1.0, v35, vcc
	v_cndmask_b32_e32 v51, 0, v51, vcc
	v_cmp_lt_i32_e32 vcc, v205, v64
	v_subrev_u32_e32 v205, 23, v167
	s_nop 0
	v_cndmask_b32_e32 v177, 1.0, v177, vcc
	v_cndmask_b32_e32 v179, 0, v179, vcc
	v_cmp_lt_i32_e32 vcc, v204, v64
	v_subrev_u32_e32 v204, 54, v167
	s_nop 0
	v_cndmask_b32_e32 v36, 1.0, v36, vcc
	v_cndmask_b32_e32 v52, 0, v52, vcc
	v_cmp_lt_i32_e32 vcc, v205, v64
	v_subrev_u32_e32 v205, 22, v167
	s_nop 0
	v_cndmask_b32_e32 v180, 1.0, v180, vcc
	v_cndmask_b32_e32 v182, 0, v182, vcc
	v_cmp_lt_i32_e32 vcc, v204, v64
	v_subrev_u32_e32 v204, 53, v167
	s_nop 0
	v_cndmask_b32_e32 v37, 1.0, v37, vcc
	v_cndmask_b32_e32 v53, 0, v53, vcc
	v_cmp_lt_i32_e32 vcc, v205, v64
	v_subrev_u32_e32 v205, 21, v167
	s_nop 0
	v_cndmask_b32_e32 v181, 1.0, v181, vcc
	v_cndmask_b32_e32 v183, 0, v183, vcc
	v_cmp_lt_i32_e32 vcc, v204, v64
	v_subrev_u32_e32 v204, 52, v167
	s_nop 0
	v_cndmask_b32_e32 v38, 1.0, v38, vcc
	v_cndmask_b32_e32 v54, 0, v54, vcc
	v_cmp_lt_i32_e32 vcc, v205, v64
	v_subrev_u32_e32 v205, 20, v167
	s_nop 0
	v_cndmask_b32_e32 v184, 1.0, v184, vcc
	v_cndmask_b32_e32 v186, 0, v186, vcc
	v_cmp_lt_i32_e32 vcc, v204, v64
	v_subrev_u32_e32 v204, 47, v167
	s_nop 0
	v_cndmask_b32_e32 v39, 1.0, v39, vcc
	v_cndmask_b32_e32 v55, 0, v55, vcc
	v_cmp_lt_i32_e32 vcc, v205, v64
	v_add_u32_e32 v205, -15, v167
	s_nop 0
	v_cndmask_b32_e32 v185, 1.0, v185, vcc
	v_cndmask_b32_e32 v187, 0, v187, vcc
	v_cmp_lt_i32_e32 vcc, v204, v64
	v_subrev_u32_e32 v204, 46, v167
	s_nop 0
	v_cndmask_b32_e32 v40, 1.0, v40, vcc
	v_cndmask_b32_e32 v56, 0, v56, vcc
	v_cmp_lt_i32_e32 vcc, v205, v64
	v_add_u32_e32 v205, -14, v167
	s_nop 0
	v_cndmask_b32_e32 v188, 1.0, v188, vcc
	v_cndmask_b32_e32 v190, 0, v190, vcc
	v_cmp_lt_i32_e32 vcc, v204, v64
	v_subrev_u32_e32 v204, 45, v167
	s_nop 0
	v_cndmask_b32_e32 v41, 1.0, v41, vcc
	v_cndmask_b32_e32 v57, 0, v57, vcc
	v_cmp_lt_i32_e32 vcc, v205, v64
	v_add_u32_e32 v205, -13, v167
	s_nop 0
	v_cndmask_b32_e32 v189, 1.0, v189, vcc
	v_cndmask_b32_e32 v191, 0, v191, vcc
	v_cmp_lt_i32_e32 vcc, v204, v64
	v_subrev_u32_e32 v204, 44, v167
	s_nop 0
	v_cndmask_b32_e32 v42, 1.0, v42, vcc
	v_cndmask_b32_e32 v58, 0, v58, vcc
	v_cmp_lt_i32_e32 vcc, v205, v64
	v_add_u32_e32 v205, -12, v167
	s_nop 0
	v_cndmask_b32_e32 v192, 1.0, v192, vcc
	v_cndmask_b32_e32 v194, 0, v194, vcc
	v_cmp_lt_i32_e32 vcc, v204, v64
	v_subrev_u32_e32 v204, 39, v167
	s_nop 0
	v_cndmask_b32_e32 v43, 1.0, v43, vcc
	v_cndmask_b32_e32 v59, 0, v59, vcc
	v_cmp_lt_i32_e32 vcc, v205, v64
	v_add_u32_e32 v205, -7, v167
	s_nop 0
	v_cndmask_b32_e32 v193, 1.0, v193, vcc
	v_cndmask_b32_e32 v195, 0, v195, vcc
	v_cmp_lt_i32_e32 vcc, v204, v64
	v_subrev_u32_e32 v204, 38, v167
	s_nop 0
	v_cndmask_b32_e32 v44, 1.0, v44, vcc
	v_cndmask_b32_e32 v60, 0, v60, vcc
	v_cmp_lt_i32_e32 vcc, v205, v64
	v_add_u32_e32 v205, -6, v167
	s_nop 0
	v_cndmask_b32_e32 v198, 1.0, v198, vcc
	v_cndmask_b32_e32 v202, 0, v202, vcc
	v_cmp_lt_i32_e32 vcc, v204, v64
	v_subrev_u32_e32 v204, 37, v167
	s_nop 0
	v_cndmask_b32_e32 v45, 1.0, v45, vcc
	v_cndmask_b32_e32 v61, 0, v61, vcc
	v_cmp_lt_i32_e32 vcc, v205, v64
	v_add_u32_e32 v205, -5, v167
	s_nop 0
	v_cndmask_b32_e32 v199, 1.0, v199, vcc
	v_cndmask_b32_e32 v203, 0, v203, vcc
	v_cmp_lt_i32_e32 vcc, v204, v64
	v_subrev_u32_e32 v204, 36, v167
	v_add_u32_e32 v167, -4, v167
	v_cndmask_b32_e32 v46, 1.0, v46, vcc
	v_cndmask_b32_e32 v62, 0, v62, vcc
	v_cmp_lt_i32_e32 vcc, v205, v64
	s_nop 1
	v_cndmask_b32_e32 v200, 1.0, v200, vcc
	v_cndmask_b32_e32 v196, 0, v196, vcc
	v_cmp_lt_i32_e32 vcc, v204, v64
	s_nop 1
	v_cndmask_b32_e32 v47, 1.0, v47, vcc
	v_cndmask_b32_e32 v63, 0, v63, vcc
	v_cmp_lt_i32_e32 vcc, v167, v64
	s_nop 1
	v_cndmask_b32_e32 v201, 1.0, v201, vcc
	v_cndmask_b32_e32 v197, 0, v197, vcc
	s_branch .LBB0_703
